# attention fast trip: next-tile K fragment reads from the first P.V gap on (gaps 1-4), early step barrier N=1
# speedup vs baseline: 1.0083x; 1.0083x over previous
.Lf3_0_486:
	ds_read_b128 v[62:65], v202 offset:16384
	ds_read_b128 v[170:173], v202 offset:18944
	s_waitcnt lgkmcnt(15)
	v_mfma_f32_32x32x16_bf16 v[18:33], v[138:141], v[178:181], v[18:33]
	v_exp_f32_e32 v98, v98
	v_exp_f32_e32 v99, v99
	v_exp_f32_e32 v100, v100
	v_exp_f32_e32 v101, v101
	ds_read_b128 v[178:181], v202 offset:18432
	ds_read_b128 v[166:169], v202 offset:20480
	s_waitcnt lgkmcnt(15)
	v_mfma_f32_32x32x16_bf16 v[2:17], v[138:141], v[174:177], v[2:17]
	v_exp_f32_e32 v102, v102
	v_exp_f32_e32 v103, v103
	v_exp_f32_e32 v104, v104
	v_exp_f32_e32 v105, v105
	ds_read_b128 v[174:177], v202 offset:16896
	ds_read_b128 v[162:165], v202 offset:20992
	s_waitcnt lgkmcnt(15)
	v_mfma_f32_32x32x16_bf16 v[18:33], v[130:133], v[66:69], v[18:33]
	v_exp_f32_e32 v106, v106
	v_exp_f32_e32 v107, v107
	v_exp_f32_e32 v108, v108
	v_exp_f32_e32 v109, v109
	ds_read_b128 v[158:161], v202 offset:22528
	ds_read_b128 v[154:157], v202 offset:23040
	s_waitcnt lgkmcnt(15)
	v_mfma_f32_32x32x16_bf16 v[2:17], v[130:133], v[70:73], v[2:17]
	v_exp_f32_e32 v110, v110
	v_exp_f32_e32 v111, v111
	v_exp_f32_e32 v112, v112
	v_exp_f32_e32 v113, v113
	s_waitcnt lgkmcnt(14)
	v_mfma_f32_32x32x16_bf16 v[18:33], v[122:125], v[74:77], v[18:33]
	v_exp_f32_e32 v82, v82
	v_exp_f32_e32 v83, v83
	v_exp_f32_e32 v84, v84
	v_exp_f32_e32 v85, v85
	s_waitcnt lgkmcnt(12)
	v_mfma_f32_32x32x16_bf16 v[2:17], v[122:125], v[50:53], v[2:17]
	v_exp_f32_e32 v86, v86
	v_exp_f32_e32 v87, v87
	v_exp_f32_e32 v88, v88
	v_exp_f32_e32 v89, v89
	s_waitcnt lgkmcnt(10)
	v_mfma_f32_32x32x16_bf16 v[18:33], v[114:117], v[54:57], v[18:33]
	v_exp_f32_e32 v90, v90
	v_exp_f32_e32 v91, v91
	v_exp_f32_e32 v92, v92
	v_exp_f32_e32 v93, v93
	s_waitcnt vmcnt(2) lgkmcnt(0)
	s_barrier
	s_waitcnt lgkmcnt(8)
	v_mfma_f32_32x32x16_bf16 v[2:17], v[114:117], v[58:61], v[2:17]
	v_exp_f32_e32 v94, v94
	v_exp_f32_e32 v95, v95
	v_exp_f32_e32 v96, v96
	v_exp_f32_e32 v97, v97

.Lf3_0_489:
	ds_read_b128 v[174:177], v202 offset:0
	ds_read_b128 v[170:173], v202 offset:512
	s_waitcnt lgkmcnt(15)
	v_mfma_f32_32x32x16_bf16 v[18:33], v[138:141], v[150:153], v[18:33]
	v_exp_f32_e32 v66, v66
	v_exp_f32_e32 v67, v67
	v_exp_f32_e32 v68, v68
	v_exp_f32_e32 v69, v69
	ds_read_b128 v[166:169], v202 offset:2048
	ds_read_b128 v[162:165], v202 offset:2560
	s_waitcnt lgkmcnt(15)
	v_mfma_f32_32x32x16_bf16 v[2:17], v[138:141], v[146:149], v[2:17]
	v_exp_f32_e32 v70, v70
	v_exp_f32_e32 v71, v71
	v_exp_f32_e32 v72, v72
	v_exp_f32_e32 v73, v73
	ds_read_b128 v[158:161], v202 offset:4096
	ds_read_b128 v[154:157], v202 offset:4608
	s_waitcnt lgkmcnt(15)
	v_mfma_f32_32x32x16_bf16 v[18:33], v[130:133], v[98:101], v[18:33]
	v_exp_f32_e32 v74, v74
	v_exp_f32_e32 v75, v75
	v_exp_f32_e32 v76, v76
	v_exp_f32_e32 v77, v77
	ds_read_b128 v[150:153], v202 offset:6144
	ds_read_b128 v[146:149], v202 offset:6656
	s_waitcnt lgkmcnt(15)
	v_mfma_f32_32x32x16_bf16 v[2:17], v[130:133], v[102:105], v[2:17]
	v_exp_f32_e32 v78, v78
	v_exp_f32_e32 v79, v79
	v_exp_f32_e32 v80, v80
	v_exp_f32_e32 v81, v81
	s_waitcnt lgkmcnt(14)
	v_mfma_f32_32x32x16_bf16 v[18:33], v[122:125], v[106:109], v[18:33]
	v_exp_f32_e32 v50, v50
	v_exp_f32_e32 v51, v51
	v_exp_f32_e32 v52, v52
	v_exp_f32_e32 v53, v53
	s_waitcnt lgkmcnt(12)
	v_mfma_f32_32x32x16_bf16 v[2:17], v[122:125], v[82:85], v[2:17]
	v_exp_f32_e32 v54, v54
	v_exp_f32_e32 v55, v55
	v_exp_f32_e32 v56, v56
	v_exp_f32_e32 v57, v57
	s_waitcnt lgkmcnt(10)
	v_mfma_f32_32x32x16_bf16 v[18:33], v[114:117], v[86:89], v[18:33]
	v_exp_f32_e32 v58, v58
	v_exp_f32_e32 v59, v59
	v_exp_f32_e32 v60, v60
	v_exp_f32_e32 v61, v61
	s_waitcnt vmcnt(2) lgkmcnt(0)
	s_barrier
	s_waitcnt lgkmcnt(8)
	v_mfma_f32_32x32x16_bf16 v[2:17], v[114:117], v[90:93], v[2:17]
	v_exp_f32_e32 v62, v62
	v_exp_f32_e32 v63, v63
	v_exp_f32_e32 v64, v64
	v_exp_f32_e32 v65, v65

.Lf3_1_486:
	ds_read_b128 v[62:65], v202 offset:8192
	ds_read_b128 v[170:173], v202 offset:10752
	s_waitcnt lgkmcnt(15)
	v_mfma_f32_32x32x16_bf16 v[18:33], v[138:141], v[178:181], v[18:33]
	v_exp_f32_e32 v98, v98
	v_exp_f32_e32 v99, v99
	v_exp_f32_e32 v100, v100
	v_exp_f32_e32 v101, v101
	ds_read_b128 v[178:181], v202 offset:10240
	ds_read_b128 v[166:169], v202 offset:12288
	s_waitcnt lgkmcnt(15)
	v_mfma_f32_32x32x16_bf16 v[2:17], v[138:141], v[174:177], v[2:17]
	v_exp_f32_e32 v102, v102
	v_exp_f32_e32 v103, v103
	v_exp_f32_e32 v104, v104
	v_exp_f32_e32 v105, v105
	ds_read_b128 v[174:177], v202 offset:8704
	ds_read_b128 v[162:165], v202 offset:12800
	s_waitcnt lgkmcnt(15)
	v_mfma_f32_32x32x16_bf16 v[18:33], v[130:133], v[66:69], v[18:33]
	v_exp_f32_e32 v106, v106
	v_exp_f32_e32 v107, v107
	v_exp_f32_e32 v108, v108
	v_exp_f32_e32 v109, v109
	ds_read_b128 v[158:161], v202 offset:14336
	ds_read_b128 v[154:157], v202 offset:14848
	s_waitcnt lgkmcnt(15)
	v_mfma_f32_32x32x16_bf16 v[2:17], v[130:133], v[70:73], v[2:17]
	v_exp_f32_e32 v110, v110
	v_exp_f32_e32 v111, v111
	v_exp_f32_e32 v112, v112
	v_exp_f32_e32 v113, v113
	s_waitcnt lgkmcnt(14)
	v_mfma_f32_32x32x16_bf16 v[18:33], v[122:125], v[74:77], v[18:33]
	v_exp_f32_e32 v82, v82
	v_exp_f32_e32 v83, v83
	v_exp_f32_e32 v84, v84
	v_exp_f32_e32 v85, v85
	s_waitcnt lgkmcnt(12)
	v_mfma_f32_32x32x16_bf16 v[2:17], v[122:125], v[50:53], v[2:17]
	v_exp_f32_e32 v86, v86
	v_exp_f32_e32 v87, v87
	v_exp_f32_e32 v88, v88
	v_exp_f32_e32 v89, v89
	s_waitcnt lgkmcnt(10)
	v_mfma_f32_32x32x16_bf16 v[18:33], v[114:117], v[54:57], v[18:33]
	v_exp_f32_e32 v90, v90
	v_exp_f32_e32 v91, v91
	v_exp_f32_e32 v92, v92
	v_exp_f32_e32 v93, v93
	s_waitcnt vmcnt(2) lgkmcnt(0)
	s_barrier
	s_waitcnt lgkmcnt(8)
	v_mfma_f32_32x32x16_bf16 v[2:17], v[114:117], v[58:61], v[2:17]
	v_exp_f32_e32 v94, v94
	v_exp_f32_e32 v95, v95
	v_exp_f32_e32 v96, v96
	v_exp_f32_e32 v97, v97

.Lf3_1_489:
	ds_read_b128 v[174:177], v202 offset:16384
	ds_read_b128 v[170:173], v202 offset:16896
	s_waitcnt lgkmcnt(15)
	v_mfma_f32_32x32x16_bf16 v[18:33], v[138:141], v[150:153], v[18:33]
	v_exp_f32_e32 v66, v66
	v_exp_f32_e32 v67, v67
	v_exp_f32_e32 v68, v68
	v_exp_f32_e32 v69, v69
	ds_read_b128 v[166:169], v202 offset:18432
	ds_read_b128 v[162:165], v202 offset:18944
	s_waitcnt lgkmcnt(15)
	v_mfma_f32_32x32x16_bf16 v[2:17], v[138:141], v[146:149], v[2:17]
	v_exp_f32_e32 v70, v70
	v_exp_f32_e32 v71, v71
	v_exp_f32_e32 v72, v72
	v_exp_f32_e32 v73, v73
	ds_read_b128 v[158:161], v202 offset:20480
	ds_read_b128 v[154:157], v202 offset:20992
	s_waitcnt lgkmcnt(15)
	v_mfma_f32_32x32x16_bf16 v[18:33], v[130:133], v[98:101], v[18:33]
	v_exp_f32_e32 v74, v74
	v_exp_f32_e32 v75, v75
	v_exp_f32_e32 v76, v76
	v_exp_f32_e32 v77, v77
	ds_read_b128 v[150:153], v202 offset:22528
	ds_read_b128 v[146:149], v202 offset:23040
	s_waitcnt lgkmcnt(15)
	v_mfma_f32_32x32x16_bf16 v[2:17], v[130:133], v[102:105], v[2:17]
	v_exp_f32_e32 v78, v78
	v_exp_f32_e32 v79, v79
	v_exp_f32_e32 v80, v80
	v_exp_f32_e32 v81, v81
	s_waitcnt lgkmcnt(14)
	v_mfma_f32_32x32x16_bf16 v[18:33], v[122:125], v[106:109], v[18:33]
	v_exp_f32_e32 v50, v50
	v_exp_f32_e32 v51, v51
	v_exp_f32_e32 v52, v52
	v_exp_f32_e32 v53, v53
	s_waitcnt lgkmcnt(12)
	v_mfma_f32_32x32x16_bf16 v[2:17], v[122:125], v[82:85], v[2:17]
	v_exp_f32_e32 v54, v54
	v_exp_f32_e32 v55, v55
	v_exp_f32_e32 v56, v56
	v_exp_f32_e32 v57, v57
	s_waitcnt lgkmcnt(10)
	v_mfma_f32_32x32x16_bf16 v[18:33], v[114:117], v[86:89], v[18:33]
	v_exp_f32_e32 v58, v58
	v_exp_f32_e32 v59, v59
	v_exp_f32_e32 v60, v60
	v_exp_f32_e32 v61, v61
	s_waitcnt vmcnt(2) lgkmcnt(0)
	s_barrier
	s_waitcnt lgkmcnt(8)
	v_mfma_f32_32x32x16_bf16 v[2:17], v[114:117], v[90:93], v[2:17]
	v_exp_f32_e32 v62, v62
	v_exp_f32_e32 v63, v63
	v_exp_f32_e32 v64, v64
	v_exp_f32_e32 v65, v65

.Lf3_2_486:
	ds_read_b128 v[62:65], v202 offset:0
	ds_read_b128 v[170:173], v202 offset:2560
	s_waitcnt lgkmcnt(15)
	v_mfma_f32_32x32x16_bf16 v[18:33], v[138:141], v[178:181], v[18:33]
	v_exp_f32_e32 v98, v98
	v_exp_f32_e32 v99, v99
	v_exp_f32_e32 v100, v100
	v_exp_f32_e32 v101, v101
	ds_read_b128 v[178:181], v202 offset:2048
	ds_read_b128 v[166:169], v202 offset:4096
	s_waitcnt lgkmcnt(15)
	v_mfma_f32_32x32x16_bf16 v[2:17], v[138:141], v[174:177], v[2:17]
	v_exp_f32_e32 v102, v102
	v_exp_f32_e32 v103, v103
	v_exp_f32_e32 v104, v104
	v_exp_f32_e32 v105, v105
	ds_read_b128 v[174:177], v202 offset:512
	ds_read_b128 v[162:165], v202 offset:4608
	s_waitcnt lgkmcnt(15)
	v_mfma_f32_32x32x16_bf16 v[18:33], v[130:133], v[66:69], v[18:33]
	v_exp_f32_e32 v106, v106
	v_exp_f32_e32 v107, v107
	v_exp_f32_e32 v108, v108
	v_exp_f32_e32 v109, v109
	ds_read_b128 v[158:161], v202 offset:6144
	ds_read_b128 v[154:157], v202 offset:6656
	s_waitcnt lgkmcnt(15)
	v_mfma_f32_32x32x16_bf16 v[2:17], v[130:133], v[70:73], v[2:17]
	v_exp_f32_e32 v110, v110
	v_exp_f32_e32 v111, v111
	v_exp_f32_e32 v112, v112
	v_exp_f32_e32 v113, v113
	s_waitcnt lgkmcnt(14)
	v_mfma_f32_32x32x16_bf16 v[18:33], v[122:125], v[74:77], v[18:33]
	v_exp_f32_e32 v82, v82
	v_exp_f32_e32 v83, v83
	v_exp_f32_e32 v84, v84
	v_exp_f32_e32 v85, v85
	s_waitcnt lgkmcnt(12)
	v_mfma_f32_32x32x16_bf16 v[2:17], v[122:125], v[50:53], v[2:17]
	v_exp_f32_e32 v86, v86
	v_exp_f32_e32 v87, v87
	v_exp_f32_e32 v88, v88
	v_exp_f32_e32 v89, v89
	s_waitcnt lgkmcnt(10)
	v_mfma_f32_32x32x16_bf16 v[18:33], v[114:117], v[54:57], v[18:33]
	v_exp_f32_e32 v90, v90
	v_exp_f32_e32 v91, v91
	v_exp_f32_e32 v92, v92
	v_exp_f32_e32 v93, v93
	s_waitcnt vmcnt(2) lgkmcnt(0)
	s_barrier
	s_waitcnt lgkmcnt(8)
	v_mfma_f32_32x32x16_bf16 v[2:17], v[114:117], v[58:61], v[2:17]
	v_exp_f32_e32 v94, v94
	v_exp_f32_e32 v95, v95
	v_exp_f32_e32 v96, v96
	v_exp_f32_e32 v97, v97

.Lf3_2_489:
	ds_read_b128 v[174:177], v202 offset:8192
	ds_read_b128 v[170:173], v202 offset:8704
	s_waitcnt lgkmcnt(15)
	v_mfma_f32_32x32x16_bf16 v[18:33], v[138:141], v[150:153], v[18:33]
	v_exp_f32_e32 v66, v66
	v_exp_f32_e32 v67, v67
	v_exp_f32_e32 v68, v68
	v_exp_f32_e32 v69, v69
	ds_read_b128 v[166:169], v202 offset:10240
	ds_read_b128 v[162:165], v202 offset:10752
	s_waitcnt lgkmcnt(15)
	v_mfma_f32_32x32x16_bf16 v[2:17], v[138:141], v[146:149], v[2:17]
	v_exp_f32_e32 v70, v70
	v_exp_f32_e32 v71, v71
	v_exp_f32_e32 v72, v72
	v_exp_f32_e32 v73, v73
	ds_read_b128 v[158:161], v202 offset:12288
	ds_read_b128 v[154:157], v202 offset:12800
	s_waitcnt lgkmcnt(15)
	v_mfma_f32_32x32x16_bf16 v[18:33], v[130:133], v[98:101], v[18:33]
	v_exp_f32_e32 v74, v74
	v_exp_f32_e32 v75, v75
	v_exp_f32_e32 v76, v76
	v_exp_f32_e32 v77, v77
	ds_read_b128 v[150:153], v202 offset:14336
	ds_read_b128 v[146:149], v202 offset:14848
	s_waitcnt lgkmcnt(15)
	v_mfma_f32_32x32x16_bf16 v[2:17], v[130:133], v[102:105], v[2:17]
	v_exp_f32_e32 v78, v78
	v_exp_f32_e32 v79, v79
	v_exp_f32_e32 v80, v80
	v_exp_f32_e32 v81, v81
	s_waitcnt lgkmcnt(14)
	v_mfma_f32_32x32x16_bf16 v[18:33], v[122:125], v[106:109], v[18:33]
	v_exp_f32_e32 v50, v50
	v_exp_f32_e32 v51, v51
	v_exp_f32_e32 v52, v52
	v_exp_f32_e32 v53, v53
	s_waitcnt lgkmcnt(12)
	v_mfma_f32_32x32x16_bf16 v[2:17], v[122:125], v[82:85], v[2:17]
	v_exp_f32_e32 v54, v54
	v_exp_f32_e32 v55, v55
	v_exp_f32_e32 v56, v56
	v_exp_f32_e32 v57, v57
	s_waitcnt lgkmcnt(10)
	v_mfma_f32_32x32x16_bf16 v[18:33], v[114:117], v[86:89], v[18:33]
	v_exp_f32_e32 v58, v58
	v_exp_f32_e32 v59, v59
	v_exp_f32_e32 v60, v60
	v_exp_f32_e32 v61, v61
	s_waitcnt vmcnt(2) lgkmcnt(0)
	s_barrier
	s_waitcnt lgkmcnt(8)
	v_mfma_f32_32x32x16_bf16 v[2:17], v[114:117], v[90:93], v[2:17]
	v_exp_f32_e32 v62, v62
	v_exp_f32_e32 v63, v63
	v_exp_f32_e32 v64, v64
	v_exp_f32_e32 v65, v65
